# adds: K-loop LDS fragment reads from one base VGPR per trip (ds_read offsets instead of per-phase v_add)
# speedup vs baseline: 1.4975x; 1.0037x over previous
.LBB0_619:
	s_ashr_i32 s39, s38, 31
	s_lshl_b64 s[2:3], s[38:39], 19
	s_add_u32 s40, s58, s2
	s_addc_u32 s41, s59, s3
	s_and_b64 s[2:3], s[36:37], exec
	s_cselect_b32 s11, s41, s31
	s_cselect_b32 s18, s40, s30
	s_ashr_i32 s13, s12, 31
	s_lshl_b64 s[2:3], s[12:13], 19
	s_add_u32 s42, s6, s2
	s_addc_u32 s43, s7, s3
	s_and_b64 s[2:3], s[36:37], exec
	s_cselect_b32 s13, s43, s17
	s_cselect_b32 s19, s42, s16
	s_add_u32 s30, s30, 0x40080
	s_addc_u32 s31, s31, 0
	s_add_u32 s28, s16, 0x100
	s_addc_u32 s29, s17, 0
	s_mov_b32 s39, -2
	s_add_u32 s2, s30, 0xfffc0080
	s_addc_u32 s3, s31, -1
	s_add_i32 s94, 32, 0x10000
	v_add_u32_e32 v131, s94, v145
	ds_read_b128 v[170:173], v131
	ds_read_b128 v[174:177], v131 offset:1024
	ds_read_b128 v[182:185], v131 offset:2048
	ds_read_b128 v[186:189], v131 offset:3072
	s_cmp_eq_u32 s39, 12
	s_cselect_b32 s3, s11, s3
	s_cselect_b32 s2, s18, s2
	s_cselect_b32 s17, s13, s29
	s_cselect_b32 s16, s19, s28
	s_add_i32 m0, s35, 0xc000
	ds_read_b128 v[190:193], v151
	ds_read_b128 v[194:197], v151 offset:1024
	ds_read_b128 v[198:201], v151 offset:2048
	ds_read_b128 v[202:205], v151 offset:3072
	ds_read_b128 v[206:209], v151 offset:4096
	ds_read_b128 v[210:213], v151 offset:5120
	ds_read_b128 v[214:217], v151 offset:6144
	ds_read_b128 v[218:221], v151 offset:7168
	global_load_lds_dwordx4 v140, s[30:31]
	s_add_i32 m0, s35, 0xe000
	s_nop 0
	global_load_lds_dwordx4 v142, s[30:31]
	s_waitcnt lgkmcnt(8)
	s_barrier
	s_waitcnt lgkmcnt(0)
	s_waitcnt lgkmcnt(0)
	v_mfma_f32_16x16x32_bf16 v[126:129], v[170:173], v[190:193], 0
	v_mfma_f32_16x16x32_bf16 v[122:125], v[182:185], v[190:193], 0
	v_mfma_f32_16x16x32_bf16 v[110:113], v[170:173], v[198:201], 0
	v_mfma_f32_16x16x32_bf16 v[106:109], v[182:185], v[198:201], 0
	v_mfma_f32_16x16x32_bf16 v[94:97], v[170:173], v[206:209], 0
	v_mfma_f32_16x16x32_bf16 v[90:93], v[182:185], v[206:209], 0
	v_mfma_f32_16x16x32_bf16 v[78:81], v[170:173], v[214:217], 0
	v_mfma_f32_16x16x32_bf16 v[74:77], v[182:185], v[214:217], 0
	v_mfma_f32_16x16x32_bf16 v[126:129], v[174:177], v[194:197], v[126:129]
	v_mfma_f32_16x16x32_bf16 v[122:125], v[186:189], v[194:197], v[122:125]
	v_mfma_f32_16x16x32_bf16 v[110:113], v[174:177], v[202:205], v[110:113]
	v_mfma_f32_16x16x32_bf16 v[106:109], v[186:189], v[202:205], v[106:109]
	v_mfma_f32_16x16x32_bf16 v[94:97], v[174:177], v[210:213], v[94:97]
	v_mfma_f32_16x16x32_bf16 v[90:93], v[186:189], v[210:213], v[90:93]
	v_mfma_f32_16x16x32_bf16 v[78:81], v[174:177], v[218:221], v[78:81]
	v_mfma_f32_16x16x32_bf16 v[74:77], v[186:189], v[218:221], v[74:77]
	s_barrier
	s_add_i32 vcc_lo, 32, 0x14000
	s_add_i32 s94, s94, s5
	s_mov_b32 m0, s94
	ds_read_b128 v[222:225], v131 offset:16384
	ds_read_b128 v[226:229], v131 offset:17408
	ds_read_b128 v[230:233], v131 offset:18432
	ds_read_b128 v[234:237], v131 offset:19456
	global_load_lds_dwordx4 v154, s[16:17]
	s_add_i32 m0, s94, 0x2000
	s_nop 0
	global_load_lds_dwordx4 v138, s[16:17]
	s_barrier
	s_waitcnt lgkmcnt(0)
	s_waitcnt lgkmcnt(0)
	v_mfma_f32_16x16x32_bf16 v[118:121], v[222:225], v[190:193], 0
	v_mfma_f32_16x16x32_bf16 v[114:117], v[230:233], v[190:193], 0
	v_mfma_f32_16x16x32_bf16 v[102:105], v[222:225], v[198:201], 0
	v_mfma_f32_16x16x32_bf16 v[98:101], v[230:233], v[198:201], 0
	v_mfma_f32_16x16x32_bf16 v[86:89], v[222:225], v[206:209], 0
	v_mfma_f32_16x16x32_bf16 v[82:85], v[230:233], v[206:209], 0
	v_mfma_f32_16x16x32_bf16 v[70:73], v[222:225], v[214:217], 0
	v_mfma_f32_16x16x32_bf16 v[66:69], v[230:233], v[214:217], 0
	v_mfma_f32_16x16x32_bf16 v[118:121], v[226:229], v[194:197], v[118:121]
	v_mfma_f32_16x16x32_bf16 v[114:117], v[234:237], v[194:197], v[114:117]
	v_mfma_f32_16x16x32_bf16 v[102:105], v[226:229], v[202:205], v[102:105]
	v_mfma_f32_16x16x32_bf16 v[98:101], v[234:237], v[202:205], v[98:101]
	v_mfma_f32_16x16x32_bf16 v[86:89], v[226:229], v[210:213], v[86:89]
	v_mfma_f32_16x16x32_bf16 v[82:85], v[234:237], v[210:213], v[82:85]
	v_mfma_f32_16x16x32_bf16 v[70:73], v[226:229], v[218:221], v[70:73]
	v_mfma_f32_16x16x32_bf16 v[66:69], v[234:237], v[218:221], v[66:69]
	s_mov_b32 m0, s35
	s_mov_b64 s[98:99], s[2:3]
	s_barrier
	ds_read_b128 v[190:193], v151 offset:16384
	ds_read_b128 v[194:197], v151 offset:17408
	ds_read_b128 v[198:201], v151 offset:18432
	ds_read_b128 v[202:205], v151 offset:19456
	ds_read_b128 v[206:209], v151 offset:20480
	ds_read_b128 v[210:213], v151 offset:21504
	ds_read_b128 v[214:217], v151 offset:22528
	ds_read_b128 v[218:221], v151 offset:23552
	global_load_lds_dwordx4 v134, s[2:3]
	s_mov_b32 m0, s14
	s_nop 0
	global_load_lds_dwordx4 v136, s[2:3]
	s_barrier
	s_waitcnt lgkmcnt(0)
	s_waitcnt lgkmcnt(0)
	v_mfma_f32_16x16x32_bf16 v[62:65], v[170:173], v[190:193], 0
	v_mfma_f32_16x16x32_bf16 v[58:61], v[182:185], v[190:193], 0
	v_mfma_f32_16x16x32_bf16 v[46:49], v[170:173], v[198:201], 0
	v_mfma_f32_16x16x32_bf16 v[42:45], v[182:185], v[198:201], 0
	v_mfma_f32_16x16x32_bf16 v[30:33], v[170:173], v[206:209], 0
	v_mfma_f32_16x16x32_bf16 v[26:29], v[182:185], v[206:209], 0
	v_mfma_f32_16x16x32_bf16 v[14:17], v[170:173], v[214:217], 0
	v_mfma_f32_16x16x32_bf16 v[10:13], v[182:185], v[214:217], 0
	v_mfma_f32_16x16x32_bf16 v[62:65], v[174:177], v[194:197], v[62:65]
	v_mfma_f32_16x16x32_bf16 v[58:61], v[186:189], v[194:197], v[58:61]
	v_mfma_f32_16x16x32_bf16 v[46:49], v[174:177], v[202:205], v[46:49]
	v_mfma_f32_16x16x32_bf16 v[42:45], v[186:189], v[202:205], v[42:45]
	v_mfma_f32_16x16x32_bf16 v[30:33], v[174:177], v[210:213], v[30:33]
	v_mfma_f32_16x16x32_bf16 v[26:29], v[186:189], v[210:213], v[26:29]
	v_mfma_f32_16x16x32_bf16 v[14:17], v[174:177], v[218:221], v[14:17]
	v_mfma_f32_16x16x32_bf16 v[10:13], v[186:189], v[218:221], v[10:13]
	s_barrier
	s_add_u32 s94, s16, 0x40000
	s_addc_u32 s95, s17, 0
	s_add_i32 vcc_lo, vcc_lo, s5
	s_mov_b32 m0, vcc_lo
	s_nop 0
	global_load_lds_dwordx4 v154, s[94:95]
	s_add_i32 m0, vcc_lo, 0x2000
	s_nop 0
	global_load_lds_dwordx4 v138, s[94:95]
	s_waitcnt vmcnt(6)
	s_barrier
	v_mfma_f32_16x16x32_bf16 v[54:57], v[222:225], v[190:193], 0
	v_mfma_f32_16x16x32_bf16 v[50:53], v[230:233], v[190:193], 0
	v_mfma_f32_16x16x32_bf16 v[38:41], v[222:225], v[198:201], 0
	v_mfma_f32_16x16x32_bf16 v[34:37], v[230:233], v[198:201], 0
	v_mfma_f32_16x16x32_bf16 v[22:25], v[222:225], v[206:209], 0
	v_mfma_f32_16x16x32_bf16 v[18:21], v[230:233], v[206:209], 0
	v_mfma_f32_16x16x32_bf16 v[6:9], v[222:225], v[214:217], 0
	v_mfma_f32_16x16x32_bf16 v[2:5], v[230:233], v[214:217], 0
	v_mfma_f32_16x16x32_bf16 v[54:57], v[226:229], v[194:197], v[54:57]
	v_mfma_f32_16x16x32_bf16 v[50:53], v[234:237], v[194:197], v[50:53]
	v_mfma_f32_16x16x32_bf16 v[38:41], v[226:229], v[202:205], v[38:41]
	v_mfma_f32_16x16x32_bf16 v[34:37], v[234:237], v[202:205], v[34:37]
	v_mfma_f32_16x16x32_bf16 v[22:25], v[226:229], v[210:213], v[22:25]
	v_mfma_f32_16x16x32_bf16 v[18:21], v[234:237], v[210:213], v[18:21]
	v_mfma_f32_16x16x32_bf16 v[6:9], v[226:229], v[218:221], v[6:9]
	v_mfma_f32_16x16x32_bf16 v[2:5], v[234:237], v[218:221], v[2:5]
	s_add_i32 s94, 32, 0x18000
	s_barrier
	ds_read_b128 v[170:173], v131 offset:32768
	ds_read_b128 v[174:177], v131 offset:33792
	ds_read_b128 v[182:185], v131 offset:34816
	ds_read_b128 v[186:189], v131 offset:35840
	s_add_u32 s2, s2, 0x40000
	s_addc_u32 s3, s3, 0
	s_mov_b32 m0, s4
	ds_read_b128 v[190:193], v151 offset:32768
	ds_read_b128 v[194:197], v151 offset:33792
	ds_read_b128 v[198:201], v151 offset:34816
	ds_read_b128 v[202:205], v151 offset:35840
	ds_read_b128 v[206:209], v151 offset:36864
	ds_read_b128 v[210:213], v151 offset:37888
	ds_read_b128 v[214:217], v151 offset:38912
	ds_read_b128 v[218:221], v151 offset:39936
	global_load_lds_dwordx4 v134, s[2:3]
	s_mov_b32 m0, s20
	s_nop 0
	global_load_lds_dwordx4 v136, s[2:3]
	s_waitcnt lgkmcnt(8)
	s_barrier
	s_waitcnt lgkmcnt(0)
	s_waitcnt lgkmcnt(0)
	v_mfma_f32_16x16x32_bf16 v[126:129], v[170:173], v[190:193], v[126:129]
	v_mfma_f32_16x16x32_bf16 v[122:125], v[182:185], v[190:193], v[122:125]
	v_mfma_f32_16x16x32_bf16 v[110:113], v[170:173], v[198:201], v[110:113]
	v_mfma_f32_16x16x32_bf16 v[106:109], v[182:185], v[198:201], v[106:109]
	v_mfma_f32_16x16x32_bf16 v[94:97], v[170:173], v[206:209], v[94:97]
	v_mfma_f32_16x16x32_bf16 v[90:93], v[182:185], v[206:209], v[90:93]
	v_mfma_f32_16x16x32_bf16 v[78:81], v[170:173], v[214:217], v[78:81]
	v_mfma_f32_16x16x32_bf16 v[74:77], v[182:185], v[214:217], v[74:77]
	v_mfma_f32_16x16x32_bf16 v[126:129], v[174:177], v[194:197], v[126:129]
	v_mfma_f32_16x16x32_bf16 v[122:125], v[186:189], v[194:197], v[122:125]
	v_mfma_f32_16x16x32_bf16 v[110:113], v[174:177], v[202:205], v[110:113]
	v_mfma_f32_16x16x32_bf16 v[106:109], v[186:189], v[202:205], v[106:109]
	v_mfma_f32_16x16x32_bf16 v[94:97], v[174:177], v[210:213], v[94:97]
	v_mfma_f32_16x16x32_bf16 v[90:93], v[186:189], v[210:213], v[90:93]
	v_mfma_f32_16x16x32_bf16 v[78:81], v[174:177], v[218:221], v[78:81]
	v_mfma_f32_16x16x32_bf16 v[74:77], v[186:189], v[218:221], v[74:77]
	s_barrier
	s_add_i32 s95, 32, 0x1c000
	s_add_i32 s2, s94, s5
	s_mov_b32 m0, s2
	ds_read_b128 v[222:225], v131 offset:49152
	ds_read_b128 v[226:229], v131 offset:50176
	ds_read_b128 v[230:233], v131 offset:51200
	ds_read_b128 v[234:237], v131 offset:52224
	s_add_u32 s100, s16, 128
	s_addc_u32 s101, s17, 0
	global_load_lds_dwordx4 v154, s[100:101]
	s_add_i32 m0, s2, 0x2000
	s_nop 0
	global_load_lds_dwordx4 v138, s[100:101]
	s_barrier
	s_waitcnt lgkmcnt(0)
	s_waitcnt lgkmcnt(0)
	v_mfma_f32_16x16x32_bf16 v[118:121], v[222:225], v[190:193], v[118:121]
	v_mfma_f32_16x16x32_bf16 v[114:117], v[230:233], v[190:193], v[114:117]
	v_mfma_f32_16x16x32_bf16 v[102:105], v[222:225], v[198:201], v[102:105]
	v_mfma_f32_16x16x32_bf16 v[98:101], v[230:233], v[198:201], v[98:101]
	v_mfma_f32_16x16x32_bf16 v[86:89], v[222:225], v[206:209], v[86:89]
	v_mfma_f32_16x16x32_bf16 v[82:85], v[230:233], v[206:209], v[82:85]
	v_mfma_f32_16x16x32_bf16 v[70:73], v[222:225], v[214:217], v[70:73]
	v_mfma_f32_16x16x32_bf16 v[66:69], v[230:233], v[214:217], v[66:69]
	v_mfma_f32_16x16x32_bf16 v[118:121], v[226:229], v[194:197], v[118:121]
	v_mfma_f32_16x16x32_bf16 v[114:117], v[234:237], v[194:197], v[114:117]
	v_mfma_f32_16x16x32_bf16 v[102:105], v[226:229], v[202:205], v[102:105]
	v_mfma_f32_16x16x32_bf16 v[98:101], v[234:237], v[202:205], v[98:101]
	v_mfma_f32_16x16x32_bf16 v[86:89], v[226:229], v[210:213], v[86:89]
	v_mfma_f32_16x16x32_bf16 v[82:85], v[234:237], v[210:213], v[82:85]
	v_mfma_f32_16x16x32_bf16 v[70:73], v[226:229], v[218:221], v[70:73]
	v_mfma_f32_16x16x32_bf16 v[66:69], v[234:237], v[218:221], v[66:69]
	s_mov_b32 m0, s21
	s_barrier
	ds_read_b128 v[190:193], v151 offset:49152
	ds_read_b128 v[194:197], v151 offset:50176
	ds_read_b128 v[198:201], v151 offset:51200
	ds_read_b128 v[202:205], v151 offset:52224
	ds_read_b128 v[206:209], v151 offset:53248
	ds_read_b128 v[210:213], v151 offset:54272
	ds_read_b128 v[214:217], v151 offset:55296
	ds_read_b128 v[218:221], v151 offset:56320
	s_add_u32 s98, s98, 128
	s_addc_u32 s99, s99, 0
	global_load_lds_dwordx4 v134, s[98:99]
	s_mov_b32 m0, s22
	s_nop 0
	global_load_lds_dwordx4 v136, s[98:99]
	s_barrier
	s_waitcnt lgkmcnt(0)
	s_waitcnt lgkmcnt(0)
	v_mfma_f32_16x16x32_bf16 v[62:65], v[170:173], v[190:193], v[62:65]
	v_mfma_f32_16x16x32_bf16 v[58:61], v[182:185], v[190:193], v[58:61]
	v_mfma_f32_16x16x32_bf16 v[46:49], v[170:173], v[198:201], v[46:49]
	v_mfma_f32_16x16x32_bf16 v[42:45], v[182:185], v[198:201], v[42:45]
	v_mfma_f32_16x16x32_bf16 v[30:33], v[170:173], v[206:209], v[30:33]
	v_mfma_f32_16x16x32_bf16 v[26:29], v[182:185], v[206:209], v[26:29]
	v_mfma_f32_16x16x32_bf16 v[14:17], v[170:173], v[214:217], v[14:17]
	v_mfma_f32_16x16x32_bf16 v[10:13], v[182:185], v[214:217], v[10:13]
	v_mfma_f32_16x16x32_bf16 v[62:65], v[174:177], v[194:197], v[62:65]
	v_mfma_f32_16x16x32_bf16 v[58:61], v[186:189], v[194:197], v[58:61]
	v_mfma_f32_16x16x32_bf16 v[46:49], v[174:177], v[202:205], v[46:49]
	v_mfma_f32_16x16x32_bf16 v[42:45], v[186:189], v[202:205], v[42:45]
	v_mfma_f32_16x16x32_bf16 v[30:33], v[174:177], v[210:213], v[30:33]
	v_mfma_f32_16x16x32_bf16 v[26:29], v[186:189], v[210:213], v[26:29]
	v_mfma_f32_16x16x32_bf16 v[14:17], v[174:177], v[218:221], v[14:17]
	v_mfma_f32_16x16x32_bf16 v[10:13], v[186:189], v[218:221], v[10:13]
	s_barrier
	s_add_u32 s2, s16, 0x40080
	s_addc_u32 s3, s17, 0
	s_add_i32 s16, s95, s5
	s_mov_b32 m0, s16
	s_nop 0
	global_load_lds_dwordx4 v154, s[2:3]
	s_add_i32 m0, s16, 0x2000
	s_nop 0
	global_load_lds_dwordx4 v138, s[2:3]
	s_waitcnt vmcnt(6)
	s_barrier
	v_mfma_f32_16x16x32_bf16 v[54:57], v[222:225], v[190:193], v[54:57]
	v_mfma_f32_16x16x32_bf16 v[50:53], v[230:233], v[190:193], v[50:53]
	v_mfma_f32_16x16x32_bf16 v[38:41], v[222:225], v[198:201], v[38:41]
	v_mfma_f32_16x16x32_bf16 v[34:37], v[230:233], v[198:201], v[34:37]
	v_mfma_f32_16x16x32_bf16 v[22:25], v[222:225], v[206:209], v[22:25]
	v_mfma_f32_16x16x32_bf16 v[18:21], v[230:233], v[206:209], v[18:21]
	v_mfma_f32_16x16x32_bf16 v[6:9], v[222:225], v[214:217], v[6:9]
	v_mfma_f32_16x16x32_bf16 v[2:5], v[230:233], v[214:217], v[2:5]
	v_mfma_f32_16x16x32_bf16 v[54:57], v[226:229], v[194:197], v[54:57]
	v_mfma_f32_16x16x32_bf16 v[50:53], v[234:237], v[194:197], v[50:53]
	v_mfma_f32_16x16x32_bf16 v[38:41], v[226:229], v[202:205], v[38:41]
	v_mfma_f32_16x16x32_bf16 v[34:37], v[234:237], v[202:205], v[34:37]
	v_mfma_f32_16x16x32_bf16 v[22:25], v[226:229], v[210:213], v[22:25]
	v_mfma_f32_16x16x32_bf16 v[18:21], v[234:237], v[210:213], v[18:21]
	v_mfma_f32_16x16x32_bf16 v[6:9], v[226:229], v[218:221], v[6:9]
	v_mfma_f32_16x16x32_bf16 v[2:5], v[234:237], v[218:221], v[2:5]
	s_add_i32 s39, s39, 2
	s_add_u32 s30, s30, 0x100
	s_addc_u32 s31, s31, 0
	s_add_u32 s28, s28, 0x100
	s_addc_u32 s29, s29, 0
	s_cmp_gt_u32 s39, 13
	s_barrier
.LBB0_620:
	s_add_u32 s2, s30, 0xfffc0080
	s_addc_u32 s3, s31, -1
	s_add_i32 s94, 32, 0x10000
	v_add_u32_e32 v131, s94, v145
	ds_read_b128 v[170:173], v131
	ds_read_b128 v[174:177], v131 offset:1024
	ds_read_b128 v[182:185], v131 offset:2048
	ds_read_b128 v[186:189], v131 offset:3072
	s_cmp_eq_u32 s39, 12
	s_cselect_b32 s3, s11, s3
	s_cselect_b32 s2, s18, s2
	s_cselect_b32 s17, s13, s29
	s_cselect_b32 s16, s19, s28
	s_add_i32 m0, s35, 0xc000
	ds_read_b128 v[190:193], v151
	ds_read_b128 v[194:197], v151 offset:1024
	ds_read_b128 v[198:201], v151 offset:2048
	ds_read_b128 v[202:205], v151 offset:3072
	ds_read_b128 v[206:209], v151 offset:4096
	ds_read_b128 v[210:213], v151 offset:5120
	ds_read_b128 v[214:217], v151 offset:6144
	ds_read_b128 v[218:221], v151 offset:7168
	global_load_lds_dwordx4 v140, s[30:31]
	s_add_i32 m0, s35, 0xe000
	s_nop 0
	global_load_lds_dwordx4 v142, s[30:31]
	s_waitcnt lgkmcnt(8)
	s_barrier
	s_waitcnt lgkmcnt(0)
	s_waitcnt lgkmcnt(0)
	v_mfma_f32_16x16x32_bf16 v[126:129], v[170:173], v[190:193], v[126:129]
	v_mfma_f32_16x16x32_bf16 v[122:125], v[182:185], v[190:193], v[122:125]
	v_mfma_f32_16x16x32_bf16 v[110:113], v[170:173], v[198:201], v[110:113]
	v_mfma_f32_16x16x32_bf16 v[106:109], v[182:185], v[198:201], v[106:109]
	v_mfma_f32_16x16x32_bf16 v[94:97], v[170:173], v[206:209], v[94:97]
	v_mfma_f32_16x16x32_bf16 v[90:93], v[182:185], v[206:209], v[90:93]
	v_mfma_f32_16x16x32_bf16 v[78:81], v[170:173], v[214:217], v[78:81]
	v_mfma_f32_16x16x32_bf16 v[74:77], v[182:185], v[214:217], v[74:77]
	v_mfma_f32_16x16x32_bf16 v[126:129], v[174:177], v[194:197], v[126:129]
	v_mfma_f32_16x16x32_bf16 v[122:125], v[186:189], v[194:197], v[122:125]
	v_mfma_f32_16x16x32_bf16 v[110:113], v[174:177], v[202:205], v[110:113]
	v_mfma_f32_16x16x32_bf16 v[106:109], v[186:189], v[202:205], v[106:109]
	v_mfma_f32_16x16x32_bf16 v[94:97], v[174:177], v[210:213], v[94:97]
	v_mfma_f32_16x16x32_bf16 v[90:93], v[186:189], v[210:213], v[90:93]
	v_mfma_f32_16x16x32_bf16 v[78:81], v[174:177], v[218:221], v[78:81]
	v_mfma_f32_16x16x32_bf16 v[74:77], v[186:189], v[218:221], v[74:77]
	s_barrier
	s_add_i32 vcc_lo, 32, 0x14000
	s_add_i32 s94, s94, s5
	s_mov_b32 m0, s94
	ds_read_b128 v[222:225], v131 offset:16384
	ds_read_b128 v[226:229], v131 offset:17408
	ds_read_b128 v[230:233], v131 offset:18432
	ds_read_b128 v[234:237], v131 offset:19456
	global_load_lds_dwordx4 v154, s[16:17]
	s_add_i32 m0, s94, 0x2000
	s_nop 0
	global_load_lds_dwordx4 v138, s[16:17]
	s_barrier
	s_waitcnt lgkmcnt(0)
	s_waitcnt lgkmcnt(0)
	v_mfma_f32_16x16x32_bf16 v[118:121], v[222:225], v[190:193], v[118:121]
	v_mfma_f32_16x16x32_bf16 v[114:117], v[230:233], v[190:193], v[114:117]
	v_mfma_f32_16x16x32_bf16 v[102:105], v[222:225], v[198:201], v[102:105]
	v_mfma_f32_16x16x32_bf16 v[98:101], v[230:233], v[198:201], v[98:101]
	v_mfma_f32_16x16x32_bf16 v[86:89], v[222:225], v[206:209], v[86:89]
	v_mfma_f32_16x16x32_bf16 v[82:85], v[230:233], v[206:209], v[82:85]
	v_mfma_f32_16x16x32_bf16 v[70:73], v[222:225], v[214:217], v[70:73]
	v_mfma_f32_16x16x32_bf16 v[66:69], v[230:233], v[214:217], v[66:69]
	v_mfma_f32_16x16x32_bf16 v[118:121], v[226:229], v[194:197], v[118:121]
	v_mfma_f32_16x16x32_bf16 v[114:117], v[234:237], v[194:197], v[114:117]
	v_mfma_f32_16x16x32_bf16 v[102:105], v[226:229], v[202:205], v[102:105]
	v_mfma_f32_16x16x32_bf16 v[98:101], v[234:237], v[202:205], v[98:101]
	v_mfma_f32_16x16x32_bf16 v[86:89], v[226:229], v[210:213], v[86:89]
	v_mfma_f32_16x16x32_bf16 v[82:85], v[234:237], v[210:213], v[82:85]
	v_mfma_f32_16x16x32_bf16 v[70:73], v[226:229], v[218:221], v[70:73]
	v_mfma_f32_16x16x32_bf16 v[66:69], v[234:237], v[218:221], v[66:69]
	s_mov_b32 m0, s35
	s_mov_b64 s[98:99], s[2:3]
	s_barrier
	ds_read_b128 v[190:193], v151 offset:16384
	ds_read_b128 v[194:197], v151 offset:17408
	ds_read_b128 v[198:201], v151 offset:18432
	ds_read_b128 v[202:205], v151 offset:19456
	ds_read_b128 v[206:209], v151 offset:20480
	ds_read_b128 v[210:213], v151 offset:21504
	ds_read_b128 v[214:217], v151 offset:22528
	ds_read_b128 v[218:221], v151 offset:23552
	global_load_lds_dwordx4 v134, s[2:3]
	s_mov_b32 m0, s14
	s_nop 0
	global_load_lds_dwordx4 v136, s[2:3]
	s_barrier
	s_waitcnt lgkmcnt(0)
	s_waitcnt lgkmcnt(0)
	v_mfma_f32_16x16x32_bf16 v[62:65], v[170:173], v[190:193], v[62:65]
	v_mfma_f32_16x16x32_bf16 v[58:61], v[182:185], v[190:193], v[58:61]
	v_mfma_f32_16x16x32_bf16 v[46:49], v[170:173], v[198:201], v[46:49]
	v_mfma_f32_16x16x32_bf16 v[42:45], v[182:185], v[198:201], v[42:45]
	v_mfma_f32_16x16x32_bf16 v[30:33], v[170:173], v[206:209], v[30:33]
	v_mfma_f32_16x16x32_bf16 v[26:29], v[182:185], v[206:209], v[26:29]
	v_mfma_f32_16x16x32_bf16 v[14:17], v[170:173], v[214:217], v[14:17]
	v_mfma_f32_16x16x32_bf16 v[10:13], v[182:185], v[214:217], v[10:13]
	v_mfma_f32_16x16x32_bf16 v[62:65], v[174:177], v[194:197], v[62:65]
	v_mfma_f32_16x16x32_bf16 v[58:61], v[186:189], v[194:197], v[58:61]
	v_mfma_f32_16x16x32_bf16 v[46:49], v[174:177], v[202:205], v[46:49]
	v_mfma_f32_16x16x32_bf16 v[42:45], v[186:189], v[202:205], v[42:45]
	v_mfma_f32_16x16x32_bf16 v[30:33], v[174:177], v[210:213], v[30:33]
	v_mfma_f32_16x16x32_bf16 v[26:29], v[186:189], v[210:213], v[26:29]
	v_mfma_f32_16x16x32_bf16 v[14:17], v[174:177], v[218:221], v[14:17]
	v_mfma_f32_16x16x32_bf16 v[10:13], v[186:189], v[218:221], v[10:13]
	s_barrier
	s_add_u32 s94, s16, 0x40000
	s_addc_u32 s95, s17, 0
	s_add_i32 vcc_lo, vcc_lo, s5
	s_mov_b32 m0, vcc_lo
	s_nop 0
	global_load_lds_dwordx4 v154, s[94:95]
	s_add_i32 m0, vcc_lo, 0x2000
	s_nop 0
	global_load_lds_dwordx4 v138, s[94:95]
	s_waitcnt vmcnt(6)
	s_barrier
	v_mfma_f32_16x16x32_bf16 v[54:57], v[222:225], v[190:193], v[54:57]
	v_mfma_f32_16x16x32_bf16 v[50:53], v[230:233], v[190:193], v[50:53]
	v_mfma_f32_16x16x32_bf16 v[38:41], v[222:225], v[198:201], v[38:41]
	v_mfma_f32_16x16x32_bf16 v[34:37], v[230:233], v[198:201], v[34:37]
	v_mfma_f32_16x16x32_bf16 v[22:25], v[222:225], v[206:209], v[22:25]
	v_mfma_f32_16x16x32_bf16 v[18:21], v[230:233], v[206:209], v[18:21]
	v_mfma_f32_16x16x32_bf16 v[6:9], v[222:225], v[214:217], v[6:9]
	v_mfma_f32_16x16x32_bf16 v[2:5], v[230:233], v[214:217], v[2:5]
	v_mfma_f32_16x16x32_bf16 v[54:57], v[226:229], v[194:197], v[54:57]
	v_mfma_f32_16x16x32_bf16 v[50:53], v[234:237], v[194:197], v[50:53]
	v_mfma_f32_16x16x32_bf16 v[38:41], v[226:229], v[202:205], v[38:41]
	v_mfma_f32_16x16x32_bf16 v[34:37], v[234:237], v[202:205], v[34:37]
	v_mfma_f32_16x16x32_bf16 v[22:25], v[226:229], v[210:213], v[22:25]
	v_mfma_f32_16x16x32_bf16 v[18:21], v[234:237], v[210:213], v[18:21]
	v_mfma_f32_16x16x32_bf16 v[6:9], v[226:229], v[218:221], v[6:9]
	v_mfma_f32_16x16x32_bf16 v[2:5], v[234:237], v[218:221], v[2:5]
	s_add_i32 s94, 32, 0x18000
	s_barrier
	ds_read_b128 v[170:173], v131 offset:32768
	ds_read_b128 v[174:177], v131 offset:33792
	ds_read_b128 v[182:185], v131 offset:34816
	ds_read_b128 v[186:189], v131 offset:35840
	s_add_u32 s2, s2, 0x40000
	s_addc_u32 s3, s3, 0
	s_mov_b32 m0, s4
	ds_read_b128 v[190:193], v151 offset:32768
	ds_read_b128 v[194:197], v151 offset:33792
	ds_read_b128 v[198:201], v151 offset:34816
	ds_read_b128 v[202:205], v151 offset:35840
	ds_read_b128 v[206:209], v151 offset:36864
	ds_read_b128 v[210:213], v151 offset:37888
	ds_read_b128 v[214:217], v151 offset:38912
	ds_read_b128 v[218:221], v151 offset:39936
	global_load_lds_dwordx4 v134, s[2:3]
	s_mov_b32 m0, s20
	s_nop 0
	global_load_lds_dwordx4 v136, s[2:3]
	s_waitcnt lgkmcnt(8)
	s_barrier
	s_waitcnt lgkmcnt(0)
	s_waitcnt lgkmcnt(0)
	v_mfma_f32_16x16x32_bf16 v[126:129], v[170:173], v[190:193], v[126:129]
	v_mfma_f32_16x16x32_bf16 v[122:125], v[182:185], v[190:193], v[122:125]
	v_mfma_f32_16x16x32_bf16 v[110:113], v[170:173], v[198:201], v[110:113]
	v_mfma_f32_16x16x32_bf16 v[106:109], v[182:185], v[198:201], v[106:109]
	v_mfma_f32_16x16x32_bf16 v[94:97], v[170:173], v[206:209], v[94:97]
	v_mfma_f32_16x16x32_bf16 v[90:93], v[182:185], v[206:209], v[90:93]
	v_mfma_f32_16x16x32_bf16 v[78:81], v[170:173], v[214:217], v[78:81]
	v_mfma_f32_16x16x32_bf16 v[74:77], v[182:185], v[214:217], v[74:77]
	v_mfma_f32_16x16x32_bf16 v[126:129], v[174:177], v[194:197], v[126:129]
	v_mfma_f32_16x16x32_bf16 v[122:125], v[186:189], v[194:197], v[122:125]
	v_mfma_f32_16x16x32_bf16 v[110:113], v[174:177], v[202:205], v[110:113]
	v_mfma_f32_16x16x32_bf16 v[106:109], v[186:189], v[202:205], v[106:109]
	v_mfma_f32_16x16x32_bf16 v[94:97], v[174:177], v[210:213], v[94:97]
	v_mfma_f32_16x16x32_bf16 v[90:93], v[186:189], v[210:213], v[90:93]
	v_mfma_f32_16x16x32_bf16 v[78:81], v[174:177], v[218:221], v[78:81]
	v_mfma_f32_16x16x32_bf16 v[74:77], v[186:189], v[218:221], v[74:77]
	s_barrier
	s_add_i32 s95, 32, 0x1c000
	s_add_i32 s2, s94, s5
	s_mov_b32 m0, s2
	ds_read_b128 v[222:225], v131 offset:49152
	ds_read_b128 v[226:229], v131 offset:50176
	ds_read_b128 v[230:233], v131 offset:51200
	ds_read_b128 v[234:237], v131 offset:52224
	s_add_u32 s100, s16, 128
	s_addc_u32 s101, s17, 0
	global_load_lds_dwordx4 v154, s[100:101]
	s_add_i32 m0, s2, 0x2000
	s_nop 0
	global_load_lds_dwordx4 v138, s[100:101]
	s_barrier
	s_waitcnt lgkmcnt(0)
	s_waitcnt lgkmcnt(0)
	v_mfma_f32_16x16x32_bf16 v[118:121], v[222:225], v[190:193], v[118:121]
	v_mfma_f32_16x16x32_bf16 v[114:117], v[230:233], v[190:193], v[114:117]
	v_mfma_f32_16x16x32_bf16 v[102:105], v[222:225], v[198:201], v[102:105]
	v_mfma_f32_16x16x32_bf16 v[98:101], v[230:233], v[198:201], v[98:101]
	v_mfma_f32_16x16x32_bf16 v[86:89], v[222:225], v[206:209], v[86:89]
	v_mfma_f32_16x16x32_bf16 v[82:85], v[230:233], v[206:209], v[82:85]
	v_mfma_f32_16x16x32_bf16 v[70:73], v[222:225], v[214:217], v[70:73]
	v_mfma_f32_16x16x32_bf16 v[66:69], v[230:233], v[214:217], v[66:69]
	v_mfma_f32_16x16x32_bf16 v[118:121], v[226:229], v[194:197], v[118:121]
	v_mfma_f32_16x16x32_bf16 v[114:117], v[234:237], v[194:197], v[114:117]
	v_mfma_f32_16x16x32_bf16 v[102:105], v[226:229], v[202:205], v[102:105]
	v_mfma_f32_16x16x32_bf16 v[98:101], v[234:237], v[202:205], v[98:101]
	v_mfma_f32_16x16x32_bf16 v[86:89], v[226:229], v[210:213], v[86:89]
	v_mfma_f32_16x16x32_bf16 v[82:85], v[234:237], v[210:213], v[82:85]
	v_mfma_f32_16x16x32_bf16 v[70:73], v[226:229], v[218:221], v[70:73]
	v_mfma_f32_16x16x32_bf16 v[66:69], v[234:237], v[218:221], v[66:69]
	s_mov_b32 m0, s21
	s_barrier
	ds_read_b128 v[190:193], v151 offset:49152
	ds_read_b128 v[194:197], v151 offset:50176
	ds_read_b128 v[198:201], v151 offset:51200
	ds_read_b128 v[202:205], v151 offset:52224
	ds_read_b128 v[206:209], v151 offset:53248
	ds_read_b128 v[210:213], v151 offset:54272
	ds_read_b128 v[214:217], v151 offset:55296
	ds_read_b128 v[218:221], v151 offset:56320
	s_add_u32 s98, s98, 128
	s_addc_u32 s99, s99, 0
	global_load_lds_dwordx4 v134, s[98:99]
	s_mov_b32 m0, s22
	s_nop 0
	global_load_lds_dwordx4 v136, s[98:99]
	s_barrier
	s_waitcnt lgkmcnt(0)
	s_waitcnt lgkmcnt(0)
	v_mfma_f32_16x16x32_bf16 v[62:65], v[170:173], v[190:193], v[62:65]
	v_mfma_f32_16x16x32_bf16 v[58:61], v[182:185], v[190:193], v[58:61]
	v_mfma_f32_16x16x32_bf16 v[46:49], v[170:173], v[198:201], v[46:49]
	v_mfma_f32_16x16x32_bf16 v[42:45], v[182:185], v[198:201], v[42:45]
	v_mfma_f32_16x16x32_bf16 v[30:33], v[170:173], v[206:209], v[30:33]
	v_mfma_f32_16x16x32_bf16 v[26:29], v[182:185], v[206:209], v[26:29]
	v_mfma_f32_16x16x32_bf16 v[14:17], v[170:173], v[214:217], v[14:17]
	v_mfma_f32_16x16x32_bf16 v[10:13], v[182:185], v[214:217], v[10:13]
	v_mfma_f32_16x16x32_bf16 v[62:65], v[174:177], v[194:197], v[62:65]
	v_mfma_f32_16x16x32_bf16 v[58:61], v[186:189], v[194:197], v[58:61]
	v_mfma_f32_16x16x32_bf16 v[46:49], v[174:177], v[202:205], v[46:49]
	v_mfma_f32_16x16x32_bf16 v[42:45], v[186:189], v[202:205], v[42:45]
	v_mfma_f32_16x16x32_bf16 v[30:33], v[174:177], v[210:213], v[30:33]
	v_mfma_f32_16x16x32_bf16 v[26:29], v[186:189], v[210:213], v[26:29]
	v_mfma_f32_16x16x32_bf16 v[14:17], v[174:177], v[218:221], v[14:17]
	v_mfma_f32_16x16x32_bf16 v[10:13], v[186:189], v[218:221], v[10:13]
	s_barrier
	s_add_u32 s2, s16, 0x40080
	s_addc_u32 s3, s17, 0
	s_add_i32 s16, s95, s5
	s_mov_b32 m0, s16
	s_nop 0
	global_load_lds_dwordx4 v154, s[2:3]
	s_add_i32 m0, s16, 0x2000
	s_nop 0
	global_load_lds_dwordx4 v138, s[2:3]
	s_waitcnt vmcnt(6)
	s_barrier
	v_mfma_f32_16x16x32_bf16 v[54:57], v[222:225], v[190:193], v[54:57]
	v_mfma_f32_16x16x32_bf16 v[50:53], v[230:233], v[190:193], v[50:53]
	v_mfma_f32_16x16x32_bf16 v[38:41], v[222:225], v[198:201], v[38:41]
	v_mfma_f32_16x16x32_bf16 v[34:37], v[230:233], v[198:201], v[34:37]
	v_mfma_f32_16x16x32_bf16 v[22:25], v[222:225], v[206:209], v[22:25]
	v_mfma_f32_16x16x32_bf16 v[18:21], v[230:233], v[206:209], v[18:21]
	v_mfma_f32_16x16x32_bf16 v[6:9], v[222:225], v[214:217], v[6:9]
	v_mfma_f32_16x16x32_bf16 v[2:5], v[230:233], v[214:217], v[2:5]
	v_mfma_f32_16x16x32_bf16 v[54:57], v[226:229], v[194:197], v[54:57]
	v_mfma_f32_16x16x32_bf16 v[50:53], v[234:237], v[194:197], v[50:53]
	v_mfma_f32_16x16x32_bf16 v[38:41], v[226:229], v[202:205], v[38:41]
	v_mfma_f32_16x16x32_bf16 v[34:37], v[234:237], v[202:205], v[34:37]
	v_mfma_f32_16x16x32_bf16 v[22:25], v[226:229], v[210:213], v[22:25]
	v_mfma_f32_16x16x32_bf16 v[18:21], v[234:237], v[210:213], v[18:21]
	v_mfma_f32_16x16x32_bf16 v[6:9], v[226:229], v[218:221], v[6:9]
	v_mfma_f32_16x16x32_bf16 v[2:5], v[234:237], v[218:221], v[2:5]
	s_add_i32 s39, s39, 2
	s_add_u32 s30, s30, 0x100
	s_addc_u32 s31, s31, 0
	s_add_u32 s28, s28, 0x100
	s_addc_u32 s29, s29, 0
	s_cmp_gt_u32 s39, 13
	s_barrier
	s_cbranch_scc0 .LBB0_620
	s_cmp_gt_i32 s10, 2
	s_cselect_b64 s[94:95], -1, 0
	s_mov_b64 s[28:29], -1
	s_and_b64 vcc, exec, s[94:95]
	s_cbranch_vccz .LBB0_638
	s_cmp_gt_u32 s10, 5
	s_mov_b64 s[30:31], -1
	s_cbranch_scc0 .LBB0_636
	s_cmp_gt_u32 s10, 8
	s_cbranch_scc0 .LBB0_633
	s_cmp_gt_u32 s10, 10
	s_mov_b64 s[2:3], -1
	s_cbranch_scc0 .LBB0_631
	s_cmp_lt_i32 s10, 12
	s_mov_b64 s[2:3], 0
	s_cbranch_scc1 .LBB0_630
	s_cmp_lg_u32 s10, 12
	s_mov_b64 s[16:17], -1
	s_cbranch_scc0 .LBB0_628
	s_mov_b64 s[16:17], 0

.LBB0_934:
	s_ashr_i32 s31, s30, 31
	v_cmp_lt_i64_e32 vcc, s[12:13], v[162:163]
	s_lshl_b64 s[12:13], s[30:31], 19
	s_add_u32 s94, s62, s12
	s_addc_u32 s95, s63, s13
	s_and_b64 s[12:13], vcc, exec
	s_cselect_b32 s31, s95, s3
	s_cselect_b32 s4, s94, s2
	s_ashr_i32 s11, s10, 31
	s_lshl_b64 s[12:13], s[10:11], 19
	s_add_u32 s16, s5, s12
	s_addc_u32 s17, s6, s13
	s_and_b64 s[12:13], vcc, exec
	s_cselect_b32 s11, s17, s35
	s_cselect_b32 vcc_lo, s16, s34
	s_add_u32 s12, s2, 0x40080
	s_addc_u32 s13, s3, 0
	s_add_u32 s34, s34, 0x100
	s_addc_u32 s35, s35, 0
	s_mov_b32 vcc_hi, -2
	s_waitcnt lgkmcnt(0)
	s_add_u32 s2, s12, 0xfffc0080
	s_addc_u32 s3, s13, -1
	s_add_i32 s38, 32, 0x10000
	v_add_u32_e32 v152, s38, v145
	ds_read_b128 v[140:143], v152
	ds_read_b128 v[148:151], v152 offset:1024
	ds_read_b128 v[164:167], v152 offset:2048
	ds_read_b128 v[168:171], v152 offset:3072
	s_cmp_eq_u32 vcc_hi, 12
	s_cselect_b32 s3, s31, s3
	s_cselect_b32 s2, s4, s2
	s_cselect_b32 s19, s11, s35
	s_cselect_b32 s18, vcc_lo, s34
	s_add_i32 m0, s14, 0xc000
	ds_read_b128 v[172:175], v147
	ds_read_b128 v[176:179], v147 offset:1024
	ds_read_b128 v[182:185], v147 offset:2048
	ds_read_b128 v[186:189], v147 offset:3072
	ds_read_b128 v[190:193], v147 offset:4096
	ds_read_b128 v[194:197], v147 offset:5120
	ds_read_b128 v[198:201], v147 offset:6144
	ds_read_b128 v[202:205], v147 offset:7168
	global_load_lds_dwordx4 v136, s[12:13]
	s_add_i32 m0, s14, 0xe000
	s_nop 0
	global_load_lds_dwordx4 v138, s[12:13]
	s_waitcnt lgkmcnt(8)
	s_barrier
	s_waitcnt lgkmcnt(0)
	s_waitcnt lgkmcnt(0)
	v_mfma_f32_16x16x32_bf16 v[126:129], v[140:143], v[172:175], 0
	v_mfma_f32_16x16x32_bf16 v[122:125], v[164:167], v[172:175], 0
	v_mfma_f32_16x16x32_bf16 v[110:113], v[140:143], v[182:185], 0
	v_mfma_f32_16x16x32_bf16 v[106:109], v[164:167], v[182:185], 0
	v_mfma_f32_16x16x32_bf16 v[94:97], v[140:143], v[190:193], 0
	v_mfma_f32_16x16x32_bf16 v[90:93], v[164:167], v[190:193], 0
	v_mfma_f32_16x16x32_bf16 v[78:81], v[140:143], v[198:201], 0
	v_mfma_f32_16x16x32_bf16 v[74:77], v[164:167], v[198:201], 0
	v_mfma_f32_16x16x32_bf16 v[126:129], v[148:151], v[176:179], v[126:129]
	v_mfma_f32_16x16x32_bf16 v[122:125], v[168:171], v[176:179], v[122:125]
	v_mfma_f32_16x16x32_bf16 v[110:113], v[148:151], v[186:189], v[110:113]
	v_mfma_f32_16x16x32_bf16 v[106:109], v[168:171], v[186:189], v[106:109]
	v_mfma_f32_16x16x32_bf16 v[94:97], v[148:151], v[194:197], v[94:97]
	v_mfma_f32_16x16x32_bf16 v[90:93], v[168:171], v[194:197], v[90:93]
	v_mfma_f32_16x16x32_bf16 v[78:81], v[148:151], v[202:205], v[78:81]
	v_mfma_f32_16x16x32_bf16 v[74:77], v[168:171], v[202:205], v[74:77]
	s_barrier
	s_add_i32 s24, 32, 0x14000
	s_add_i32 s38, s38, s7
	ds_read_b128 v[206:209], v152 offset:16384
	ds_read_b128 v[210:213], v152 offset:17408
	ds_read_b128 v[214:217], v152 offset:18432
	ds_read_b128 v[218:221], v152 offset:19456
	s_mov_b32 m0, s38
	s_nop 0
	global_load_lds_dwordx4 v154, s[18:19]
	s_add_i32 m0, s38, 0x2000
	s_nop 0
	global_load_lds_dwordx4 v130, s[18:19]
	s_barrier
	s_waitcnt lgkmcnt(0)
	s_waitcnt lgkmcnt(0)
	v_mfma_f32_16x16x32_bf16 v[118:121], v[206:209], v[172:175], 0
	v_mfma_f32_16x16x32_bf16 v[114:117], v[214:217], v[172:175], 0
	v_mfma_f32_16x16x32_bf16 v[102:105], v[206:209], v[182:185], 0
	v_mfma_f32_16x16x32_bf16 v[98:101], v[214:217], v[182:185], 0
	v_mfma_f32_16x16x32_bf16 v[86:89], v[206:209], v[190:193], 0
	v_mfma_f32_16x16x32_bf16 v[82:85], v[214:217], v[190:193], 0
	v_mfma_f32_16x16x32_bf16 v[70:73], v[206:209], v[198:201], 0
	v_mfma_f32_16x16x32_bf16 v[66:69], v[214:217], v[198:201], 0
	v_mfma_f32_16x16x32_bf16 v[118:121], v[210:213], v[176:179], v[118:121]
	v_mfma_f32_16x16x32_bf16 v[114:117], v[218:221], v[176:179], v[114:117]
	v_mfma_f32_16x16x32_bf16 v[102:105], v[210:213], v[186:189], v[102:105]
	v_mfma_f32_16x16x32_bf16 v[98:101], v[218:221], v[186:189], v[98:101]
	v_mfma_f32_16x16x32_bf16 v[86:89], v[210:213], v[194:197], v[86:89]
	v_mfma_f32_16x16x32_bf16 v[82:85], v[218:221], v[194:197], v[82:85]
	v_mfma_f32_16x16x32_bf16 v[70:73], v[210:213], v[202:205], v[70:73]
	v_mfma_f32_16x16x32_bf16 v[66:69], v[218:221], v[202:205], v[66:69]
	s_mov_b32 m0, s14
	s_mov_b64 s[98:99], s[2:3]
	s_barrier
	ds_read_b128 v[172:175], v147 offset:16384
	ds_read_b128 v[176:179], v147 offset:17408
	ds_read_b128 v[182:185], v147 offset:18432
	ds_read_b128 v[186:189], v147 offset:19456
	ds_read_b128 v[190:193], v147 offset:20480
	ds_read_b128 v[194:197], v147 offset:21504
	ds_read_b128 v[198:201], v147 offset:22528
	ds_read_b128 v[202:205], v147 offset:23552
	global_load_lds_dwordx4 v134, s[2:3]
	s_mov_b32 m0, s20
	s_nop 0
	global_load_lds_dwordx4 v132, s[2:3]
	s_barrier
	s_waitcnt lgkmcnt(0)
	s_waitcnt lgkmcnt(0)
	v_mfma_f32_16x16x32_bf16 v[62:65], v[140:143], v[172:175], 0
	v_mfma_f32_16x16x32_bf16 v[58:61], v[164:167], v[172:175], 0
	v_mfma_f32_16x16x32_bf16 v[46:49], v[140:143], v[182:185], 0
	v_mfma_f32_16x16x32_bf16 v[42:45], v[164:167], v[182:185], 0
	v_mfma_f32_16x16x32_bf16 v[30:33], v[140:143], v[190:193], 0
	v_mfma_f32_16x16x32_bf16 v[26:29], v[164:167], v[190:193], 0
	v_mfma_f32_16x16x32_bf16 v[14:17], v[140:143], v[198:201], 0
	v_mfma_f32_16x16x32_bf16 v[10:13], v[164:167], v[198:201], 0
	v_mfma_f32_16x16x32_bf16 v[62:65], v[148:151], v[176:179], v[62:65]
	v_mfma_f32_16x16x32_bf16 v[58:61], v[168:171], v[176:179], v[58:61]
	v_mfma_f32_16x16x32_bf16 v[46:49], v[148:151], v[186:189], v[46:49]
	v_mfma_f32_16x16x32_bf16 v[42:45], v[168:171], v[186:189], v[42:45]
	v_mfma_f32_16x16x32_bf16 v[30:33], v[148:151], v[194:197], v[30:33]
	v_mfma_f32_16x16x32_bf16 v[26:29], v[168:171], v[194:197], v[26:29]
	v_mfma_f32_16x16x32_bf16 v[14:17], v[148:151], v[202:205], v[14:17]
	v_mfma_f32_16x16x32_bf16 v[10:13], v[168:171], v[202:205], v[10:13]
	s_barrier
	s_add_u32 s38, s18, 0x40000
	s_addc_u32 s39, s19, 0
	s_add_i32 s24, s24, s7
	s_mov_b32 m0, s24
	s_nop 0
	global_load_lds_dwordx4 v154, s[38:39]
	s_add_i32 m0, s24, 0x2000
	s_nop 0
	global_load_lds_dwordx4 v130, s[38:39]
	s_waitcnt vmcnt(6)
	s_barrier
	v_mfma_f32_16x16x32_bf16 v[54:57], v[206:209], v[172:175], 0
	v_mfma_f32_16x16x32_bf16 v[50:53], v[214:217], v[172:175], 0
	v_mfma_f32_16x16x32_bf16 v[38:41], v[206:209], v[182:185], 0
	v_mfma_f32_16x16x32_bf16 v[34:37], v[214:217], v[182:185], 0
	v_mfma_f32_16x16x32_bf16 v[22:25], v[206:209], v[190:193], 0
	v_mfma_f32_16x16x32_bf16 v[18:21], v[214:217], v[190:193], 0
	v_mfma_f32_16x16x32_bf16 v[6:9], v[206:209], v[198:201], 0
	v_mfma_f32_16x16x32_bf16 v[2:5], v[214:217], v[198:201], 0
	v_mfma_f32_16x16x32_bf16 v[54:57], v[210:213], v[176:179], v[54:57]
	v_mfma_f32_16x16x32_bf16 v[50:53], v[218:221], v[176:179], v[50:53]
	v_mfma_f32_16x16x32_bf16 v[38:41], v[210:213], v[186:189], v[38:41]
	v_mfma_f32_16x16x32_bf16 v[34:37], v[218:221], v[186:189], v[34:37]
	v_mfma_f32_16x16x32_bf16 v[22:25], v[210:213], v[194:197], v[22:25]
	v_mfma_f32_16x16x32_bf16 v[18:21], v[218:221], v[194:197], v[18:21]
	v_mfma_f32_16x16x32_bf16 v[6:9], v[210:213], v[202:205], v[6:9]
	v_mfma_f32_16x16x32_bf16 v[2:5], v[218:221], v[202:205], v[2:5]
	s_add_i32 s24, 32, 0x18000
	s_barrier
	ds_read_b128 v[140:143], v152 offset:32768
	ds_read_b128 v[148:151], v152 offset:33792
	ds_read_b128 v[164:167], v152 offset:34816
	ds_read_b128 v[168:171], v152 offset:35840
	s_add_u32 s2, s2, 0x40000
	s_addc_u32 s3, s3, 0
	s_mov_b32 m0, s21
	ds_read_b128 v[172:175], v147 offset:32768
	ds_read_b128 v[176:179], v147 offset:33792
	ds_read_b128 v[182:185], v147 offset:34816
	ds_read_b128 v[186:189], v147 offset:35840
	ds_read_b128 v[190:193], v147 offset:36864
	ds_read_b128 v[194:197], v147 offset:37888
	ds_read_b128 v[198:201], v147 offset:38912
	ds_read_b128 v[202:205], v147 offset:39936
	global_load_lds_dwordx4 v134, s[2:3]
	s_mov_b32 m0, s22
	s_nop 0
	global_load_lds_dwordx4 v132, s[2:3]
	s_waitcnt lgkmcnt(8)
	s_barrier
	s_waitcnt lgkmcnt(0)
	s_waitcnt lgkmcnt(0)
	v_mfma_f32_16x16x32_bf16 v[126:129], v[140:143], v[172:175], v[126:129]
	v_mfma_f32_16x16x32_bf16 v[122:125], v[164:167], v[172:175], v[122:125]
	v_mfma_f32_16x16x32_bf16 v[110:113], v[140:143], v[182:185], v[110:113]
	v_mfma_f32_16x16x32_bf16 v[106:109], v[164:167], v[182:185], v[106:109]
	v_mfma_f32_16x16x32_bf16 v[94:97], v[140:143], v[190:193], v[94:97]
	v_mfma_f32_16x16x32_bf16 v[90:93], v[164:167], v[190:193], v[90:93]
	v_mfma_f32_16x16x32_bf16 v[78:81], v[140:143], v[198:201], v[78:81]
	v_mfma_f32_16x16x32_bf16 v[74:77], v[164:167], v[198:201], v[74:77]
	v_mfma_f32_16x16x32_bf16 v[126:129], v[148:151], v[176:179], v[126:129]
	v_mfma_f32_16x16x32_bf16 v[122:125], v[168:171], v[176:179], v[122:125]
	v_mfma_f32_16x16x32_bf16 v[110:113], v[148:151], v[186:189], v[110:113]
	v_mfma_f32_16x16x32_bf16 v[106:109], v[168:171], v[186:189], v[106:109]
	v_mfma_f32_16x16x32_bf16 v[94:97], v[148:151], v[194:197], v[94:97]
	v_mfma_f32_16x16x32_bf16 v[90:93], v[168:171], v[194:197], v[90:93]
	v_mfma_f32_16x16x32_bf16 v[78:81], v[148:151], v[202:205], v[78:81]
	v_mfma_f32_16x16x32_bf16 v[74:77], v[168:171], v[202:205], v[74:77]
	s_barrier
	s_add_i32 s38, 32, 0x1c000
	s_add_i32 s2, s24, s7
	s_mov_b32 m0, s2
	ds_read_b128 v[206:209], v152 offset:49152
	ds_read_b128 v[210:213], v152 offset:50176
	ds_read_b128 v[214:217], v152 offset:51200
	ds_read_b128 v[218:221], v152 offset:52224
	s_add_u32 s100, s18, 128
	s_addc_u32 s101, s19, 0
	global_load_lds_dwordx4 v154, s[100:101]
	s_add_i32 m0, s2, 0x2000
	s_nop 0
	global_load_lds_dwordx4 v130, s[100:101]
	s_barrier
	s_waitcnt lgkmcnt(0)
	s_waitcnt lgkmcnt(0)
	v_mfma_f32_16x16x32_bf16 v[118:121], v[206:209], v[172:175], v[118:121]
	v_mfma_f32_16x16x32_bf16 v[114:117], v[214:217], v[172:175], v[114:117]
	v_mfma_f32_16x16x32_bf16 v[102:105], v[206:209], v[182:185], v[102:105]
	v_mfma_f32_16x16x32_bf16 v[98:101], v[214:217], v[182:185], v[98:101]
	v_mfma_f32_16x16x32_bf16 v[86:89], v[206:209], v[190:193], v[86:89]
	v_mfma_f32_16x16x32_bf16 v[82:85], v[214:217], v[190:193], v[82:85]
	v_mfma_f32_16x16x32_bf16 v[70:73], v[206:209], v[198:201], v[70:73]
	v_mfma_f32_16x16x32_bf16 v[66:69], v[214:217], v[198:201], v[66:69]
	v_mfma_f32_16x16x32_bf16 v[118:121], v[210:213], v[176:179], v[118:121]
	v_mfma_f32_16x16x32_bf16 v[114:117], v[218:221], v[176:179], v[114:117]
	v_mfma_f32_16x16x32_bf16 v[102:105], v[210:213], v[186:189], v[102:105]
	v_mfma_f32_16x16x32_bf16 v[98:101], v[218:221], v[186:189], v[98:101]
	v_mfma_f32_16x16x32_bf16 v[86:89], v[210:213], v[194:197], v[86:89]
	v_mfma_f32_16x16x32_bf16 v[82:85], v[218:221], v[194:197], v[82:85]
	v_mfma_f32_16x16x32_bf16 v[70:73], v[210:213], v[202:205], v[70:73]
	v_mfma_f32_16x16x32_bf16 v[66:69], v[218:221], v[202:205], v[66:69]
	s_mov_b32 m0, s23
	s_barrier
	ds_read_b128 v[172:175], v147 offset:49152
	ds_read_b128 v[176:179], v147 offset:50176
	ds_read_b128 v[182:185], v147 offset:51200
	ds_read_b128 v[186:189], v147 offset:52224
	ds_read_b128 v[190:193], v147 offset:53248
	ds_read_b128 v[194:197], v147 offset:54272
	ds_read_b128 v[198:201], v147 offset:55296
	ds_read_b128 v[202:205], v147 offset:56320
	s_add_u32 s98, s98, 128
	s_addc_u32 s99, s99, 0
	global_load_lds_dwordx4 v134, s[98:99]
	s_mov_b32 m0, s28
	s_nop 0
	global_load_lds_dwordx4 v132, s[98:99]
	s_barrier
	s_waitcnt lgkmcnt(0)
	s_waitcnt lgkmcnt(0)
	v_mfma_f32_16x16x32_bf16 v[62:65], v[140:143], v[172:175], v[62:65]
	v_mfma_f32_16x16x32_bf16 v[58:61], v[164:167], v[172:175], v[58:61]
	v_mfma_f32_16x16x32_bf16 v[46:49], v[140:143], v[182:185], v[46:49]
	v_mfma_f32_16x16x32_bf16 v[42:45], v[164:167], v[182:185], v[42:45]
	v_mfma_f32_16x16x32_bf16 v[30:33], v[140:143], v[190:193], v[30:33]
	v_mfma_f32_16x16x32_bf16 v[26:29], v[164:167], v[190:193], v[26:29]
	v_mfma_f32_16x16x32_bf16 v[14:17], v[140:143], v[198:201], v[14:17]
	v_mfma_f32_16x16x32_bf16 v[10:13], v[164:167], v[198:201], v[10:13]
	v_mfma_f32_16x16x32_bf16 v[62:65], v[148:151], v[176:179], v[62:65]
	v_mfma_f32_16x16x32_bf16 v[58:61], v[168:171], v[176:179], v[58:61]
	v_mfma_f32_16x16x32_bf16 v[46:49], v[148:151], v[186:189], v[46:49]
	v_mfma_f32_16x16x32_bf16 v[42:45], v[168:171], v[186:189], v[42:45]
	v_mfma_f32_16x16x32_bf16 v[30:33], v[148:151], v[194:197], v[30:33]
	v_mfma_f32_16x16x32_bf16 v[26:29], v[168:171], v[194:197], v[26:29]
	v_mfma_f32_16x16x32_bf16 v[14:17], v[148:151], v[202:205], v[14:17]
	v_mfma_f32_16x16x32_bf16 v[10:13], v[168:171], v[202:205], v[10:13]
	s_barrier
	s_add_u32 s2, s18, 0x40080
	s_addc_u32 s3, s19, 0
	s_add_i32 s18, s38, s7
	s_mov_b32 m0, s18
	s_nop 0
	global_load_lds_dwordx4 v154, s[2:3]
	s_add_i32 m0, s18, 0x2000
	s_nop 0
	global_load_lds_dwordx4 v130, s[2:3]
	s_waitcnt vmcnt(6)
	s_barrier
	v_mfma_f32_16x16x32_bf16 v[54:57], v[206:209], v[172:175], v[54:57]
	v_mfma_f32_16x16x32_bf16 v[50:53], v[214:217], v[172:175], v[50:53]
	v_mfma_f32_16x16x32_bf16 v[38:41], v[206:209], v[182:185], v[38:41]
	v_mfma_f32_16x16x32_bf16 v[34:37], v[214:217], v[182:185], v[34:37]
	v_mfma_f32_16x16x32_bf16 v[22:25], v[206:209], v[190:193], v[22:25]
	v_mfma_f32_16x16x32_bf16 v[18:21], v[214:217], v[190:193], v[18:21]
	v_mfma_f32_16x16x32_bf16 v[6:9], v[206:209], v[198:201], v[6:9]
	v_mfma_f32_16x16x32_bf16 v[2:5], v[214:217], v[198:201], v[2:5]
	v_mfma_f32_16x16x32_bf16 v[54:57], v[210:213], v[176:179], v[54:57]
	v_mfma_f32_16x16x32_bf16 v[50:53], v[218:221], v[176:179], v[50:53]
	v_mfma_f32_16x16x32_bf16 v[38:41], v[210:213], v[186:189], v[38:41]
	v_mfma_f32_16x16x32_bf16 v[34:37], v[218:221], v[186:189], v[34:37]
	v_mfma_f32_16x16x32_bf16 v[22:25], v[210:213], v[194:197], v[22:25]
	v_mfma_f32_16x16x32_bf16 v[18:21], v[218:221], v[194:197], v[18:21]
	v_mfma_f32_16x16x32_bf16 v[6:9], v[210:213], v[202:205], v[6:9]
	v_mfma_f32_16x16x32_bf16 v[2:5], v[218:221], v[202:205], v[2:5]
	s_add_i32 vcc_hi, vcc_hi, 2
	s_add_u32 s12, s12, 0x100
	s_addc_u32 s13, s13, 0
	s_add_u32 s34, s34, 0x100
	s_addc_u32 s35, s35, 0
	s_cmp_gt_u32 vcc_hi, 13
	s_barrier
.LBB0_935:
	s_add_u32 s2, s12, 0xfffc0080
	s_addc_u32 s3, s13, -1
	s_add_i32 s38, 32, 0x10000
	v_add_u32_e32 v152, s38, v145
	ds_read_b128 v[140:143], v152
	ds_read_b128 v[148:151], v152 offset:1024
	ds_read_b128 v[164:167], v152 offset:2048
	ds_read_b128 v[168:171], v152 offset:3072
	s_cmp_eq_u32 vcc_hi, 12
	s_cselect_b32 s3, s31, s3
	s_cselect_b32 s2, s4, s2
	s_cselect_b32 s19, s11, s35
	s_cselect_b32 s18, vcc_lo, s34
	s_add_i32 m0, s14, 0xc000
	ds_read_b128 v[172:175], v147
	ds_read_b128 v[176:179], v147 offset:1024
	ds_read_b128 v[182:185], v147 offset:2048
	ds_read_b128 v[186:189], v147 offset:3072
	ds_read_b128 v[190:193], v147 offset:4096
	ds_read_b128 v[194:197], v147 offset:5120
	ds_read_b128 v[198:201], v147 offset:6144
	ds_read_b128 v[202:205], v147 offset:7168
	global_load_lds_dwordx4 v136, s[12:13]
	s_add_i32 m0, s14, 0xe000
	s_nop 0
	global_load_lds_dwordx4 v138, s[12:13]
	s_waitcnt lgkmcnt(8)
	s_barrier
	s_waitcnt lgkmcnt(0)
	s_waitcnt lgkmcnt(0)
	v_mfma_f32_16x16x32_bf16 v[126:129], v[140:143], v[172:175], v[126:129]
	v_mfma_f32_16x16x32_bf16 v[122:125], v[164:167], v[172:175], v[122:125]
	v_mfma_f32_16x16x32_bf16 v[110:113], v[140:143], v[182:185], v[110:113]
	v_mfma_f32_16x16x32_bf16 v[106:109], v[164:167], v[182:185], v[106:109]
	v_mfma_f32_16x16x32_bf16 v[94:97], v[140:143], v[190:193], v[94:97]
	v_mfma_f32_16x16x32_bf16 v[90:93], v[164:167], v[190:193], v[90:93]
	v_mfma_f32_16x16x32_bf16 v[78:81], v[140:143], v[198:201], v[78:81]
	v_mfma_f32_16x16x32_bf16 v[74:77], v[164:167], v[198:201], v[74:77]
	v_mfma_f32_16x16x32_bf16 v[126:129], v[148:151], v[176:179], v[126:129]
	v_mfma_f32_16x16x32_bf16 v[122:125], v[168:171], v[176:179], v[122:125]
	v_mfma_f32_16x16x32_bf16 v[110:113], v[148:151], v[186:189], v[110:113]
	v_mfma_f32_16x16x32_bf16 v[106:109], v[168:171], v[186:189], v[106:109]
	v_mfma_f32_16x16x32_bf16 v[94:97], v[148:151], v[194:197], v[94:97]
	v_mfma_f32_16x16x32_bf16 v[90:93], v[168:171], v[194:197], v[90:93]
	v_mfma_f32_16x16x32_bf16 v[78:81], v[148:151], v[202:205], v[78:81]
	v_mfma_f32_16x16x32_bf16 v[74:77], v[168:171], v[202:205], v[74:77]
	s_barrier
	s_add_i32 s24, 32, 0x14000
	s_add_i32 s38, s38, s7
	ds_read_b128 v[206:209], v152 offset:16384
	ds_read_b128 v[210:213], v152 offset:17408
	ds_read_b128 v[214:217], v152 offset:18432
	ds_read_b128 v[218:221], v152 offset:19456
	s_mov_b32 m0, s38
	s_nop 0
	global_load_lds_dwordx4 v154, s[18:19]
	s_add_i32 m0, s38, 0x2000
	s_nop 0
	global_load_lds_dwordx4 v130, s[18:19]
	s_barrier
	s_waitcnt lgkmcnt(0)
	s_waitcnt lgkmcnt(0)
	v_mfma_f32_16x16x32_bf16 v[118:121], v[206:209], v[172:175], v[118:121]
	v_mfma_f32_16x16x32_bf16 v[114:117], v[214:217], v[172:175], v[114:117]
	v_mfma_f32_16x16x32_bf16 v[102:105], v[206:209], v[182:185], v[102:105]
	v_mfma_f32_16x16x32_bf16 v[98:101], v[214:217], v[182:185], v[98:101]
	v_mfma_f32_16x16x32_bf16 v[86:89], v[206:209], v[190:193], v[86:89]
	v_mfma_f32_16x16x32_bf16 v[82:85], v[214:217], v[190:193], v[82:85]
	v_mfma_f32_16x16x32_bf16 v[70:73], v[206:209], v[198:201], v[70:73]
	v_mfma_f32_16x16x32_bf16 v[66:69], v[214:217], v[198:201], v[66:69]
	v_mfma_f32_16x16x32_bf16 v[118:121], v[210:213], v[176:179], v[118:121]
	v_mfma_f32_16x16x32_bf16 v[114:117], v[218:221], v[176:179], v[114:117]
	v_mfma_f32_16x16x32_bf16 v[102:105], v[210:213], v[186:189], v[102:105]
	v_mfma_f32_16x16x32_bf16 v[98:101], v[218:221], v[186:189], v[98:101]
	v_mfma_f32_16x16x32_bf16 v[86:89], v[210:213], v[194:197], v[86:89]
	v_mfma_f32_16x16x32_bf16 v[82:85], v[218:221], v[194:197], v[82:85]
	v_mfma_f32_16x16x32_bf16 v[70:73], v[210:213], v[202:205], v[70:73]
	v_mfma_f32_16x16x32_bf16 v[66:69], v[218:221], v[202:205], v[66:69]
	s_mov_b32 m0, s14
	s_mov_b64 s[98:99], s[2:3]
	s_barrier
	ds_read_b128 v[172:175], v147 offset:16384
	ds_read_b128 v[176:179], v147 offset:17408
	ds_read_b128 v[182:185], v147 offset:18432
	ds_read_b128 v[186:189], v147 offset:19456
	ds_read_b128 v[190:193], v147 offset:20480
	ds_read_b128 v[194:197], v147 offset:21504
	ds_read_b128 v[198:201], v147 offset:22528
	ds_read_b128 v[202:205], v147 offset:23552
	global_load_lds_dwordx4 v134, s[2:3]
	s_mov_b32 m0, s20
	s_nop 0
	global_load_lds_dwordx4 v132, s[2:3]
	s_barrier
	s_waitcnt lgkmcnt(0)
	s_waitcnt lgkmcnt(0)
	v_mfma_f32_16x16x32_bf16 v[62:65], v[140:143], v[172:175], v[62:65]
	v_mfma_f32_16x16x32_bf16 v[58:61], v[164:167], v[172:175], v[58:61]
	v_mfma_f32_16x16x32_bf16 v[46:49], v[140:143], v[182:185], v[46:49]
	v_mfma_f32_16x16x32_bf16 v[42:45], v[164:167], v[182:185], v[42:45]
	v_mfma_f32_16x16x32_bf16 v[30:33], v[140:143], v[190:193], v[30:33]
	v_mfma_f32_16x16x32_bf16 v[26:29], v[164:167], v[190:193], v[26:29]
	v_mfma_f32_16x16x32_bf16 v[14:17], v[140:143], v[198:201], v[14:17]
	v_mfma_f32_16x16x32_bf16 v[10:13], v[164:167], v[198:201], v[10:13]
	v_mfma_f32_16x16x32_bf16 v[62:65], v[148:151], v[176:179], v[62:65]
	v_mfma_f32_16x16x32_bf16 v[58:61], v[168:171], v[176:179], v[58:61]
	v_mfma_f32_16x16x32_bf16 v[46:49], v[148:151], v[186:189], v[46:49]
	v_mfma_f32_16x16x32_bf16 v[42:45], v[168:171], v[186:189], v[42:45]
	v_mfma_f32_16x16x32_bf16 v[30:33], v[148:151], v[194:197], v[30:33]
	v_mfma_f32_16x16x32_bf16 v[26:29], v[168:171], v[194:197], v[26:29]
	v_mfma_f32_16x16x32_bf16 v[14:17], v[148:151], v[202:205], v[14:17]
	v_mfma_f32_16x16x32_bf16 v[10:13], v[168:171], v[202:205], v[10:13]
	s_barrier
	s_add_u32 s38, s18, 0x40000
	s_addc_u32 s39, s19, 0
	s_add_i32 s24, s24, s7
	s_mov_b32 m0, s24
	s_nop 0
	global_load_lds_dwordx4 v154, s[38:39]
	s_add_i32 m0, s24, 0x2000
	s_nop 0
	global_load_lds_dwordx4 v130, s[38:39]
	s_waitcnt vmcnt(6)
	s_barrier
	v_mfma_f32_16x16x32_bf16 v[54:57], v[206:209], v[172:175], v[54:57]
	v_mfma_f32_16x16x32_bf16 v[50:53], v[214:217], v[172:175], v[50:53]
	v_mfma_f32_16x16x32_bf16 v[38:41], v[206:209], v[182:185], v[38:41]
	v_mfma_f32_16x16x32_bf16 v[34:37], v[214:217], v[182:185], v[34:37]
	v_mfma_f32_16x16x32_bf16 v[22:25], v[206:209], v[190:193], v[22:25]
	v_mfma_f32_16x16x32_bf16 v[18:21], v[214:217], v[190:193], v[18:21]
	v_mfma_f32_16x16x32_bf16 v[6:9], v[206:209], v[198:201], v[6:9]
	v_mfma_f32_16x16x32_bf16 v[2:5], v[214:217], v[198:201], v[2:5]
	v_mfma_f32_16x16x32_bf16 v[54:57], v[210:213], v[176:179], v[54:57]
	v_mfma_f32_16x16x32_bf16 v[50:53], v[218:221], v[176:179], v[50:53]
	v_mfma_f32_16x16x32_bf16 v[38:41], v[210:213], v[186:189], v[38:41]
	v_mfma_f32_16x16x32_bf16 v[34:37], v[218:221], v[186:189], v[34:37]
	v_mfma_f32_16x16x32_bf16 v[22:25], v[210:213], v[194:197], v[22:25]
	v_mfma_f32_16x16x32_bf16 v[18:21], v[218:221], v[194:197], v[18:21]
	v_mfma_f32_16x16x32_bf16 v[6:9], v[210:213], v[202:205], v[6:9]
	v_mfma_f32_16x16x32_bf16 v[2:5], v[218:221], v[202:205], v[2:5]
	s_add_i32 s24, 32, 0x18000
	s_barrier
	ds_read_b128 v[140:143], v152 offset:32768
	ds_read_b128 v[148:151], v152 offset:33792
	ds_read_b128 v[164:167], v152 offset:34816
	ds_read_b128 v[168:171], v152 offset:35840
	s_add_u32 s2, s2, 0x40000
	s_addc_u32 s3, s3, 0
	s_mov_b32 m0, s21
	ds_read_b128 v[172:175], v147 offset:32768
	ds_read_b128 v[176:179], v147 offset:33792
	ds_read_b128 v[182:185], v147 offset:34816
	ds_read_b128 v[186:189], v147 offset:35840
	ds_read_b128 v[190:193], v147 offset:36864
	ds_read_b128 v[194:197], v147 offset:37888
	ds_read_b128 v[198:201], v147 offset:38912
	ds_read_b128 v[202:205], v147 offset:39936
	global_load_lds_dwordx4 v134, s[2:3]
	s_mov_b32 m0, s22
	s_nop 0
	global_load_lds_dwordx4 v132, s[2:3]
	s_waitcnt lgkmcnt(8)
	s_barrier
	s_waitcnt lgkmcnt(0)
	s_waitcnt lgkmcnt(0)
	v_mfma_f32_16x16x32_bf16 v[126:129], v[140:143], v[172:175], v[126:129]
	v_mfma_f32_16x16x32_bf16 v[122:125], v[164:167], v[172:175], v[122:125]
	v_mfma_f32_16x16x32_bf16 v[110:113], v[140:143], v[182:185], v[110:113]
	v_mfma_f32_16x16x32_bf16 v[106:109], v[164:167], v[182:185], v[106:109]
	v_mfma_f32_16x16x32_bf16 v[94:97], v[140:143], v[190:193], v[94:97]
	v_mfma_f32_16x16x32_bf16 v[90:93], v[164:167], v[190:193], v[90:93]
	v_mfma_f32_16x16x32_bf16 v[78:81], v[140:143], v[198:201], v[78:81]
	v_mfma_f32_16x16x32_bf16 v[74:77], v[164:167], v[198:201], v[74:77]
	v_mfma_f32_16x16x32_bf16 v[126:129], v[148:151], v[176:179], v[126:129]
	v_mfma_f32_16x16x32_bf16 v[122:125], v[168:171], v[176:179], v[122:125]
	v_mfma_f32_16x16x32_bf16 v[110:113], v[148:151], v[186:189], v[110:113]
	v_mfma_f32_16x16x32_bf16 v[106:109], v[168:171], v[186:189], v[106:109]
	v_mfma_f32_16x16x32_bf16 v[94:97], v[148:151], v[194:197], v[94:97]
	v_mfma_f32_16x16x32_bf16 v[90:93], v[168:171], v[194:197], v[90:93]
	v_mfma_f32_16x16x32_bf16 v[78:81], v[148:151], v[202:205], v[78:81]
	v_mfma_f32_16x16x32_bf16 v[74:77], v[168:171], v[202:205], v[74:77]
	s_barrier
	s_add_i32 s38, 32, 0x1c000
	s_add_i32 s2, s24, s7
	s_mov_b32 m0, s2
	ds_read_b128 v[206:209], v152 offset:49152
	ds_read_b128 v[210:213], v152 offset:50176
	ds_read_b128 v[214:217], v152 offset:51200
	ds_read_b128 v[218:221], v152 offset:52224
	s_add_u32 s100, s18, 128
	s_addc_u32 s101, s19, 0
	global_load_lds_dwordx4 v154, s[100:101]
	s_add_i32 m0, s2, 0x2000
	s_nop 0
	global_load_lds_dwordx4 v130, s[100:101]
	s_barrier
	s_waitcnt lgkmcnt(0)
	s_waitcnt lgkmcnt(0)
	v_mfma_f32_16x16x32_bf16 v[118:121], v[206:209], v[172:175], v[118:121]
	v_mfma_f32_16x16x32_bf16 v[114:117], v[214:217], v[172:175], v[114:117]
	v_mfma_f32_16x16x32_bf16 v[102:105], v[206:209], v[182:185], v[102:105]
	v_mfma_f32_16x16x32_bf16 v[98:101], v[214:217], v[182:185], v[98:101]
	v_mfma_f32_16x16x32_bf16 v[86:89], v[206:209], v[190:193], v[86:89]
	v_mfma_f32_16x16x32_bf16 v[82:85], v[214:217], v[190:193], v[82:85]
	v_mfma_f32_16x16x32_bf16 v[70:73], v[206:209], v[198:201], v[70:73]
	v_mfma_f32_16x16x32_bf16 v[66:69], v[214:217], v[198:201], v[66:69]
	v_mfma_f32_16x16x32_bf16 v[118:121], v[210:213], v[176:179], v[118:121]
	v_mfma_f32_16x16x32_bf16 v[114:117], v[218:221], v[176:179], v[114:117]
	v_mfma_f32_16x16x32_bf16 v[102:105], v[210:213], v[186:189], v[102:105]
	v_mfma_f32_16x16x32_bf16 v[98:101], v[218:221], v[186:189], v[98:101]
	v_mfma_f32_16x16x32_bf16 v[86:89], v[210:213], v[194:197], v[86:89]
	v_mfma_f32_16x16x32_bf16 v[82:85], v[218:221], v[194:197], v[82:85]
	v_mfma_f32_16x16x32_bf16 v[70:73], v[210:213], v[202:205], v[70:73]
	v_mfma_f32_16x16x32_bf16 v[66:69], v[218:221], v[202:205], v[66:69]
	s_mov_b32 m0, s23
	s_barrier
	ds_read_b128 v[172:175], v147 offset:49152
	ds_read_b128 v[176:179], v147 offset:50176
	ds_read_b128 v[182:185], v147 offset:51200
	ds_read_b128 v[186:189], v147 offset:52224
	ds_read_b128 v[190:193], v147 offset:53248
	ds_read_b128 v[194:197], v147 offset:54272
	ds_read_b128 v[198:201], v147 offset:55296
	ds_read_b128 v[202:205], v147 offset:56320
	s_add_u32 s98, s98, 128
	s_addc_u32 s99, s99, 0
	global_load_lds_dwordx4 v134, s[98:99]
	s_mov_b32 m0, s28
	s_nop 0
	global_load_lds_dwordx4 v132, s[98:99]
	s_barrier
	s_waitcnt lgkmcnt(0)
	s_waitcnt lgkmcnt(0)
	v_mfma_f32_16x16x32_bf16 v[62:65], v[140:143], v[172:175], v[62:65]
	v_mfma_f32_16x16x32_bf16 v[58:61], v[164:167], v[172:175], v[58:61]
	v_mfma_f32_16x16x32_bf16 v[46:49], v[140:143], v[182:185], v[46:49]
	v_mfma_f32_16x16x32_bf16 v[42:45], v[164:167], v[182:185], v[42:45]
	v_mfma_f32_16x16x32_bf16 v[30:33], v[140:143], v[190:193], v[30:33]
	v_mfma_f32_16x16x32_bf16 v[26:29], v[164:167], v[190:193], v[26:29]
	v_mfma_f32_16x16x32_bf16 v[14:17], v[140:143], v[198:201], v[14:17]
	v_mfma_f32_16x16x32_bf16 v[10:13], v[164:167], v[198:201], v[10:13]
	v_mfma_f32_16x16x32_bf16 v[62:65], v[148:151], v[176:179], v[62:65]
	v_mfma_f32_16x16x32_bf16 v[58:61], v[168:171], v[176:179], v[58:61]
	v_mfma_f32_16x16x32_bf16 v[46:49], v[148:151], v[186:189], v[46:49]
	v_mfma_f32_16x16x32_bf16 v[42:45], v[168:171], v[186:189], v[42:45]
	v_mfma_f32_16x16x32_bf16 v[30:33], v[148:151], v[194:197], v[30:33]
	v_mfma_f32_16x16x32_bf16 v[26:29], v[168:171], v[194:197], v[26:29]
	v_mfma_f32_16x16x32_bf16 v[14:17], v[148:151], v[202:205], v[14:17]
	v_mfma_f32_16x16x32_bf16 v[10:13], v[168:171], v[202:205], v[10:13]
	s_barrier
	s_add_u32 s2, s18, 0x40080
	s_addc_u32 s3, s19, 0
	s_add_i32 s18, s38, s7
	s_mov_b32 m0, s18
	s_nop 0
	global_load_lds_dwordx4 v154, s[2:3]
	s_add_i32 m0, s18, 0x2000
	s_nop 0
	global_load_lds_dwordx4 v130, s[2:3]
	s_waitcnt vmcnt(6)
	s_barrier
	v_mfma_f32_16x16x32_bf16 v[54:57], v[206:209], v[172:175], v[54:57]
	v_mfma_f32_16x16x32_bf16 v[50:53], v[214:217], v[172:175], v[50:53]
	v_mfma_f32_16x16x32_bf16 v[38:41], v[206:209], v[182:185], v[38:41]
	v_mfma_f32_16x16x32_bf16 v[34:37], v[214:217], v[182:185], v[34:37]
	v_mfma_f32_16x16x32_bf16 v[22:25], v[206:209], v[190:193], v[22:25]
	v_mfma_f32_16x16x32_bf16 v[18:21], v[214:217], v[190:193], v[18:21]
	v_mfma_f32_16x16x32_bf16 v[6:9], v[206:209], v[198:201], v[6:9]
	v_mfma_f32_16x16x32_bf16 v[2:5], v[214:217], v[198:201], v[2:5]
	v_mfma_f32_16x16x32_bf16 v[54:57], v[210:213], v[176:179], v[54:57]
	v_mfma_f32_16x16x32_bf16 v[50:53], v[218:221], v[176:179], v[50:53]
	v_mfma_f32_16x16x32_bf16 v[38:41], v[210:213], v[186:189], v[38:41]
	v_mfma_f32_16x16x32_bf16 v[34:37], v[218:221], v[186:189], v[34:37]
	v_mfma_f32_16x16x32_bf16 v[22:25], v[210:213], v[194:197], v[22:25]
	v_mfma_f32_16x16x32_bf16 v[18:21], v[218:221], v[194:197], v[18:21]
	v_mfma_f32_16x16x32_bf16 v[6:9], v[210:213], v[202:205], v[6:9]
	v_mfma_f32_16x16x32_bf16 v[2:5], v[218:221], v[202:205], v[2:5]
	s_add_i32 vcc_hi, vcc_hi, 2
	s_add_u32 s12, s12, 0x100
	s_addc_u32 s13, s13, 0
	s_add_u32 s34, s34, 0x100
	s_addc_u32 s35, s35, 0
	s_cmp_gt_u32 vcc_hi, 13
	s_barrier
	s_cbranch_scc0 .LBB0_935
	v_lshl_add_u32 v142, s36, 8, v144
	v_ashrrev_i32_e32 v143, 31, v142
	v_lshl_or_b32 v140, s37, 8, v146
	v_lshlrev_b64 v[150:151], 11, v[142:143]
	v_ashrrev_i32_e32 v141, 31, v140
	v_lshl_add_u64 v[150:151], s[58:59], 0, v[150:151]
	v_lshl_add_u64 v[164:165], v[140:141], 1, v[150:151]
	v_mov_b64_e32 v[238:239], v[164:165]
	global_load_dwordx4 v[150:153], v[164:165], off
	s_nop 0
	global_load_dwordx4 v[164:167], v[164:165], off offset:256
	v_add_co_u32_e32 v240, vcc, 0x8000, v238
	s_nop 1
	v_addc_co_u32_e32 v241, vcc, 0, v239, vcc
	global_load_dwordx4 v[182:185], v[240:241], off
	global_load_dwordx4 v[186:189], v[240:241], off offset:256
	v_add_co_u32_e32 v240, vcc, 0x10000, v238
	s_nop 1
	v_addc_co_u32_e32 v241, vcc, 0, v239, vcc
	global_load_dwordx4 v[190:193], v[240:241], off
	global_load_dwordx4 v[194:197], v[240:241], off offset:256
	v_add_co_u32_e32 v240, vcc, 0x18000, v238
	s_nop 1
	v_addc_co_u32_e32 v241, vcc, 0, v239, vcc
	global_load_dwordx4 v[198:201], v[240:241], off
	global_load_dwordx4 v[202:205], v[240:241], off offset:256
	v_add_co_u32_e32 v240, vcc, 0x40000, v238
	s_nop 1
	v_addc_co_u32_e32 v241, vcc, 0, v239, vcc
	global_load_dwordx4 v[206:209], v[240:241], off
	global_load_dwordx4 v[210:213], v[240:241], off offset:256
	v_add_co_u32_e32 v240, vcc, 0x48000, v238
	s_nop 1
	v_addc_co_u32_e32 v241, vcc, 0, v239, vcc
	global_load_dwordx4 v[214:217], v[240:241], off
	global_load_dwordx4 v[218:221], v[240:241], off offset:256
	v_add_co_u32_e32 v240, vcc, 0x50000, v238
	s_nop 1
	v_addc_co_u32_e32 v241, vcc, 0, v239, vcc
	global_load_dwordx4 v[222:225], v[240:241], off
	global_load_dwordx4 v[226:229], v[240:241], off offset:256
	v_add_co_u32_e32 v240, vcc, 0x58000, v238
	s_nop 1
	v_addc_co_u32_e32 v241, vcc, 0, v239, vcc
	global_load_dwordx4 v[230:233], v[240:241], off
	global_load_dwordx4 v[234:237], v[240:241], off offset:256
	v_lshlrev_b32_e32 v148, 1, v140
	s_waitcnt vmcnt(14)
	v_lshlrev_b32_e32 v149, 16, v150
	v_lshlrev_b32_e32 v171, 16, v164
	v_and_b32_e32 v164, 0xffff0000, v164
	v_and_b32_e32 v150, 0xffff0000, v150
	v_lshlrev_b32_e32 v168, 16, v151
	v_and_b32_e32 v151, 0xffff0000, v151
	v_lshlrev_b32_e32 v173, 16, v166
	v_and_b32_e32 v166, 0xffff0000, v166
	v_lshlrev_b32_e32 v174, 16, v167
	v_and_b32_e32 v167, 0xffff0000, v167
	v_add_f32_e32 v118, v118, v171
	v_add_f32_e32 v119, v119, v164
	v_lshlrev_b32_e32 v172, 16, v165
	v_add_f32_e32 v126, v126, v149
	v_add_f32_e32 v149, v114, v173
	v_add_f32_e32 v114, v127, v150
	v_add_f32_e32 v127, v115, v166
	v_add_f32_e32 v115, v128, v168
	v_add_f32_e32 v128, v116, v174
	v_add_f32_e32 v116, v129, v151
	v_add_f32_e32 v129, v117, v167
	v_mul_f32_e32 v117, v118, v118
	v_mul_f32_e32 v150, v119, v119
	v_add_f32_e32 v120, v120, v172
	v_fmac_f32_e32 v117, v126, v126
	v_fmac_f32_e32 v150, v114, v114
	v_and_b32_e32 v165, 0xffff0000, v165
	v_add_f32_e32 v117, v117, v150
	v_mul_f32_e32 v150, v120, v120
	v_add_f32_e32 v121, v121, v165
	v_fmac_f32_e32 v150, v115, v115
	v_add_f32_e32 v117, v150, v117
	v_mul_f32_e32 v150, v121, v121
	v_lshlrev_b32_e32 v169, 16, v152
	v_fmac_f32_e32 v150, v116, v116
	v_add_f32_e32 v122, v122, v169
	v_add_f32_e32 v117, v150, v117
	v_mul_f32_e32 v150, v149, v149
	v_and_b32_e32 v152, 0xffff0000, v152
	v_fmac_f32_e32 v150, v122, v122
	v_add_f32_e32 v123, v123, v152
	v_add_f32_e32 v117, v150, v117
	v_mul_f32_e32 v150, v127, v127
	v_lshlrev_b32_e32 v170, 16, v153
	v_fmac_f32_e32 v150, v123, v123
	v_add_f32_e32 v124, v124, v170
	v_add_f32_e32 v117, v150, v117
	v_mul_f32_e32 v150, v128, v128
	v_and_b32_e32 v153, 0xffff0000, v153
	v_fmac_f32_e32 v150, v124, v124
	v_add_f32_e32 v125, v125, v153
	v_add_f32_e32 v117, v150, v117
	v_mul_f32_e32 v150, v129, v129
	v_fmac_f32_e32 v150, v125, v125
	v_lshl_add_u32 v151, v142, 11, v148
	v_cvt_pk_bf16_f32 v114, v126, v114
	v_cvt_pk_bf16_f32 v115, v115, v116
	v_add_f32_e32 v150, v150, v117
	v_cvt_pk_bf16_f32 v116, v122, v123
	v_cvt_pk_bf16_f32 v117, v124, v125
	buffer_store_dwordx4 v[114:117], v151, s[64:67], 0 offen sc1
	s_nop 1
	v_cvt_pk_bf16_f32 v114, v118, v119
	v_cvt_pk_bf16_f32 v115, v120, v121
	v_cvt_pk_bf16_f32 v116, v149, v127
	v_cvt_pk_bf16_f32 v117, v128, v129
	buffer_store_dwordx4 v[114:117], v151, s[64:67], 0 offen offset:256 sc1
	s_nop 1
	v_and_b32_e32 v115, 64, v181
	v_xor_b32_e32 v114, 16, v181
	v_add_u32_e32 v115, 64, v115
	v_cmp_lt_i32_e32 vcc, v114, v115
	v_xor_b32_e32 v117, 32, v181
	s_nop 0
	v_cndmask_b32_e32 v114, v181, v114, vcc
	v_lshlrev_b32_e32 v116, 2, v114
	ds_bpermute_b32 v114, v116, v150
	v_cmp_lt_i32_e32 vcc, v117, v115
	s_waitcnt lgkmcnt(0)
	v_add_f32_e32 v114, v150, v114
	v_cndmask_b32_e32 v115, v181, v117, vcc
	v_lshlrev_b32_e32 v117, 2, v115
	ds_bpermute_b32 v115, v117, v114
	s_and_saveexec_b64 s[2:3], s[40:41]
	s_cbranch_execz .LBB0_938
	v_lshl_add_u64 v[118:119], v[142:143], 2, s[0:1]
	s_waitcnt lgkmcnt(0)
	v_add_f32_e32 v114, v114, v115
	global_atomic_add_f32 v[118:119], v114, off
